# grid barrier leader: acquire invalidate issued before the L2 write-back so it is hidden behind the write-back and the TOP arrival round trip
# speedup vs baseline: 1.0041x; 1.0014x over previous
.LBB0_151:
	s_andn2_saveexec_b64 s[4:5], s[10:11]
	s_cbranch_execz .LBB0_171
	s_mov_b64 s[10:11], exec
	buffer_inv sc1
	buffer_wbl2 sc1
	s_waitcnt lgkmcnt(0)
	s_waitcnt vmcnt(0)
	v_mbcnt_lo_u32_b32 v2, s10, 0
	v_mbcnt_hi_u32_b32 v2, s11, v2
	v_cmp_eq_u32_e32 vcc, 0, v2
	s_and_saveexec_b64 s[12:13], vcc
	s_cbranch_execz .LBB0_154
	s_bcnt1_i32_b64 s3, s[10:11]
	v_mov_b32_e32 v3, 0x7000
	v_mov_b32_e32 v4, s3
	global_atomic_add v3, v3, v4, s[72:73] offset:1024 sc0

.LBB0_297:
	s_andn2_saveexec_b64 s[4:5], s[8:9]
	s_cbranch_execz .LBB0_317
	s_mov_b64 s[8:9], exec
	buffer_inv sc1
	buffer_wbl2 sc1
	s_waitcnt lgkmcnt(0)
	s_waitcnt vmcnt(0)
	v_mbcnt_lo_u32_b32 v2, s8, 0
	v_mbcnt_hi_u32_b32 v2, s9, v2
	v_cmp_eq_u32_e32 vcc, 0, v2
	s_and_saveexec_b64 s[10:11], vcc
	s_cbranch_execz .LBB0_300
	s_bcnt1_i32_b64 s3, s[8:9]
	v_mov_b32_e32 v3, 0x7000
	v_mov_b32_e32 v4, s3
	global_atomic_add v3, v3, v4, s[72:73] offset:1024 sc0

.LBB0_490:
	s_andn2_saveexec_b64 s[4:5], s[12:13]
	s_cbranch_execz .LBB0_510
	s_mov_b64 s[12:13], exec
	buffer_inv sc1
	buffer_wbl2 sc1
	s_waitcnt lgkmcnt(0)
	s_waitcnt vmcnt(0)
	v_mbcnt_lo_u32_b32 v2, s12, 0
	v_mbcnt_hi_u32_b32 v2, s13, v2
	v_cmp_eq_u32_e32 vcc, 0, v2
	s_and_saveexec_b64 s[14:15], vcc
	s_cbranch_execz .LBB0_493
	s_bcnt1_i32_b64 s3, s[12:13]
	v_mov_b32_e32 v3, 0x7000
	v_mov_b32_e32 v4, s3
	global_atomic_add v3, v3, v4, s[72:73] offset:1024 sc0

.LBB0_1626:
	s_andn2_saveexec_b64 s[4:5], s[10:11]
	s_cbranch_execz .LBB0_1646
	s_mov_b64 s[10:11], exec
	buffer_inv sc1
	buffer_wbl2 sc1
	s_waitcnt lgkmcnt(0)
	s_waitcnt vmcnt(0)
	v_mbcnt_lo_u32_b32 v1, s10, 0
	v_mbcnt_hi_u32_b32 v1, s11, v1
	v_cmp_eq_u32_e32 vcc, 0, v1
	s_and_saveexec_b64 s[12:13], vcc
	s_cbranch_execz .LBB0_1629
	s_bcnt1_i32_b64 s3, s[10:11]
	v_mov_b32_e32 v2, 0x7000
	v_mov_b32_e32 v3, s3
	global_atomic_add v2, v2, v3, s[72:73] offset:1024 sc0

.LBB0_1736:
	s_andn2_saveexec_b64 s[4:5], s[12:13]
	s_cbranch_execz .LBB0_1756
	s_mov_b64 s[12:13], exec
	buffer_inv sc1
	buffer_wbl2 sc1
	s_waitcnt lgkmcnt(0)
	s_waitcnt vmcnt(0)
	v_mbcnt_lo_u32_b32 v1, s12, 0
	v_mbcnt_hi_u32_b32 v1, s13, v1
	v_cmp_eq_u32_e32 vcc, 0, v1
	s_and_saveexec_b64 s[14:15], vcc
	s_cbranch_execz .LBB0_1739
	s_bcnt1_i32_b64 s3, s[12:13]
	v_mov_b32_e32 v2, 0x7000
	v_mov_b32_e32 v3, s3
	global_atomic_add v2, v2, v3, s[72:73] offset:1024 sc0

.LBB0_1977:
	s_andn2_saveexec_b64 s[16:17], s[16:17]
	s_cbranch_execz .LBB0_1997
	s_mov_b64 s[16:17], exec
	buffer_inv sc1
	buffer_wbl2 sc1
	s_waitcnt lgkmcnt(0)
	s_waitcnt vmcnt(0)
	v_mbcnt_lo_u32_b32 v1, s16, 0
	v_mbcnt_hi_u32_b32 v1, s17, v1
	v_cmp_eq_u32_e32 vcc, 0, v1
	s_and_saveexec_b64 s[20:21], vcc
	s_cbranch_execz .LBB0_1980
	s_bcnt1_i32_b64 s3, s[16:17]
	v_mov_b32_e32 v2, 0x7000
	v_mov_b32_e32 v3, s3
	global_atomic_add v2, v2, v3, s[72:73] offset:1024 sc0
